# attention: SGPR-base K/V prefetch addressing, two row-sum accumulator pairs per half (shorter pk_add chains)
# baseline (speedup 1.0000x reference)
.LBB0_609:
	global_load_dwordx4 v[146:149], v[160:161], off
	global_load_dwordx4 v[150:153], v[162:163], off
	v_lshl_add_u64 v[160:161], v[160:161], 0, s[54:55]
	v_lshl_add_u64 v[162:163], v[162:163], 0, s[88:89]
	s_nop 0
	v_readfirstlane_b32 s0, v160
	v_readfirstlane_b32 s1, v161
	v_readfirstlane_b32 s100, v162
	v_readfirstlane_b32 s101, v163
	s_nop 3
	v_subrev_u32_e32 v192, s0, v160
	v_subrev_u32_e32 v193, s100, v162
	ds_read_b128 v[164:167], v175 offset:0
	ds_read_b128 v[168:171], v175 offset:32
	ds_read_b128 v[226:229], v174 offset:10240
	ds_read_b128 v[234:237], v174 offset:14848
	ds_read_b128 v[230:233], v174 offset:10272
	ds_read_b128 v[238:241], v174 offset:14880
	v_mov_b32_e32 v184, 0
	v_mov_b32_e32 v185, 0
	v_mov_b32_e32 v186, 0
	v_mov_b32_e32 v187, 0
	v_mov_b32_e32 v188, 0
	v_mov_b32_e32 v189, 0
	v_mov_b32_e32 v190, 0
	v_mov_b32_e32 v191, 0
	v_mov_b32_e32 v200, 0
	v_mov_b32_e32 v201, 0
	v_mov_b32_e32 v202, 0
	v_mov_b32_e32 v203, 0
	v_mov_b32_e32 v204, 0
	v_mov_b32_e32 v205, 0
	v_mov_b32_e32 v208, 0
	v_mov_b32_e32 v209, 0
	s_waitcnt lgkmcnt(5)
	v_mfma_f32_32x32x16_bf16 v[96:111], v[164:167], v[130:133], v[64:79]
	s_waitcnt lgkmcnt(4)
	v_mfma_f32_32x32x16_bf16 v[96:111], v[168:171], v[134:137], v[96:111]
	ds_read_b128 v[164:167], v175 offset:5120
	ds_read_b128 v[168:171], v175 offset:5152
	s_waitcnt vmcnt(1)
	ds_write_b128 v155, v[146:149] offset:19456
	s_waitcnt vmcnt(0)
	ds_write_b128 v157, v[150:153] offset:29696
	s_mov_b32 s2, 0
	s_waitcnt lgkmcnt(0)
	s_barrier
.Lat_loop:
	global_load_dwordx4 v[146:149], v192, s[0:1]
	global_load_dwordx4 v[150:153], v193, s[100:101]
	s_add_u32 s0, s0, s54
	s_addc_u32 s1, s1, s55
	s_add_u32 s100, s100, s88
	s_addc_u32 s101, s101, s89
	s_waitcnt lgkmcnt(2)
	v_mfma_f32_32x32x16_bf16 v[112:127], v[164:167], v[138:141], v[80:95]
	v_exp_f32_e32 v96, v96
	v_exp_f32_e32 v97, v97
	v_mfma_f32_32x32x16_bf16 v[112:127], v[168:171], v[142:145], v[112:127]
	ds_read_b128 v[164:167], v175 offset:2560
	ds_read_b128 v[168:171], v175 offset:2592
	v_exp_f32_e32 v98, v98
	v_exp_f32_e32 v99, v99
	v_exp_f32_e32 v100, v100
	v_mfma_f32_32x32x16_bf16 v[32:47], v[226:229], v[184:187], v[32:47]
	ds_read_b128 v[226:229], v174 offset:10240
	v_exp_f32_e32 v101, v101
	v_exp_f32_e32 v102, v102
	v_exp_f32_e32 v103, v103
	v_mfma_f32_32x32x16_bf16 v[0:15], v[234:237], v[184:187], v[0:15]
	ds_read_b128 v[234:237], v174 offset:14848
	v_exp_f32_e32 v104, v104
	v_exp_f32_e32 v105, v105
	v_exp_f32_e32 v106, v106
	v_mfma_f32_32x32x16_bf16 v[32:47], v[230:233], v[188:191], v[32:47]
	ds_read_b128 v[230:233], v174 offset:10272
	v_exp_f32_e32 v107, v107
	v_exp_f32_e32 v108, v108
	v_exp_f32_e32 v109, v109
	v_mfma_f32_32x32x16_bf16 v[0:15], v[238:241], v[188:191], v[0:15]
	ds_read_b128 v[238:241], v174 offset:14880
	v_exp_f32_e32 v110, v110
	v_exp_f32_e32 v111, v111
	v_pk_add_f32 v[200:201], v[96:97], v[200:201]
	v_cvt_pk_bf16_f32 v176, v96, v97
	v_pk_add_f32 v[204:205], v[98:99], v[204:205]
	v_cvt_pk_bf16_f32 v177, v98, v99
	v_pk_add_f32 v[200:201], v[100:101], v[200:201]
	v_cvt_pk_bf16_f32 v178, v100, v101
	v_pk_add_f32 v[204:205], v[102:103], v[204:205]
	v_cvt_pk_bf16_f32 v179, v102, v103
	v_pk_add_f32 v[200:201], v[104:105], v[200:201]
	v_cvt_pk_bf16_f32 v180, v104, v105
	v_pk_add_f32 v[204:205], v[106:107], v[204:205]
	v_cvt_pk_bf16_f32 v181, v106, v107
	v_pk_add_f32 v[200:201], v[108:109], v[200:201]
	v_cvt_pk_bf16_f32 v182, v108, v109
	v_pk_add_f32 v[204:205], v[110:111], v[204:205]
	v_cvt_pk_bf16_f32 v183, v110, v111
	s_waitcnt lgkmcnt(4)
	v_mfma_f32_32x32x16_bf16 v[96:111], v[164:167], v[130:133], v[64:79]
	v_exp_f32_e32 v112, v112
	v_exp_f32_e32 v113, v113
	v_mfma_f32_32x32x16_bf16 v[96:111], v[168:171], v[134:137], v[96:111]
	ds_read_b128 v[164:167], v175 offset:7680
	ds_read_b128 v[168:171], v175 offset:7712
	v_exp_f32_e32 v114, v114
	v_exp_f32_e32 v115, v115
	v_exp_f32_e32 v116, v116
	s_waitcnt lgkmcnt(2)
	v_mfma_f32_32x32x16_bf16 v[48:63], v[226:229], v[176:179], v[48:63]
	v_exp_f32_e32 v117, v117
	v_exp_f32_e32 v118, v118
	v_exp_f32_e32 v119, v119
	v_mfma_f32_32x32x16_bf16 v[16:31], v[234:237], v[176:179], v[16:31]
	v_exp_f32_e32 v120, v120
	v_exp_f32_e32 v121, v121
	v_exp_f32_e32 v122, v122
	v_mfma_f32_32x32x16_bf16 v[48:63], v[230:233], v[180:183], v[48:63]
	v_exp_f32_e32 v123, v123
	v_exp_f32_e32 v124, v124
	v_exp_f32_e32 v125, v125
	v_mfma_f32_32x32x16_bf16 v[16:31], v[238:241], v[180:183], v[16:31]
	v_exp_f32_e32 v126, v126
	v_exp_f32_e32 v127, v127
	v_pk_add_f32 v[202:203], v[112:113], v[202:203]
	v_cvt_pk_bf16_f32 v184, v112, v113
	v_pk_add_f32 v[208:209], v[114:115], v[208:209]
	v_cvt_pk_bf16_f32 v185, v114, v115
	v_pk_add_f32 v[202:203], v[116:117], v[202:203]
	v_cvt_pk_bf16_f32 v186, v116, v117
	v_pk_add_f32 v[208:209], v[118:119], v[208:209]
	v_cvt_pk_bf16_f32 v187, v118, v119
	v_pk_add_f32 v[202:203], v[120:121], v[202:203]
	v_cvt_pk_bf16_f32 v188, v120, v121
	v_pk_add_f32 v[208:209], v[122:123], v[208:209]
	v_cvt_pk_bf16_f32 v189, v122, v123
	v_pk_add_f32 v[202:203], v[124:125], v[202:203]
	v_cvt_pk_bf16_f32 v190, v124, v125
	v_pk_add_f32 v[208:209], v[126:127], v[208:209]
	v_cvt_pk_bf16_f32 v191, v126, v127
	s_waitcnt lgkmcnt(0)
	v_mfma_f32_32x32x16_bf16 v[112:127], v[164:167], v[138:141], v[80:95]
	v_exp_f32_e32 v96, v96
	v_exp_f32_e32 v97, v97
	v_mfma_f32_32x32x16_bf16 v[112:127], v[168:171], v[142:145], v[112:127]
	s_barrier
	ds_read_b128 v[164:167], v175 offset:19456
	ds_read_b128 v[168:171], v175 offset:19488
	v_exp_f32_e32 v98, v98
	v_exp_f32_e32 v99, v99
	v_exp_f32_e32 v100, v100
	v_mfma_f32_32x32x16_bf16 v[32:47], v[226:229], v[184:187], v[32:47]
	ds_read_b128 v[226:229], v174 offset:10304
	v_exp_f32_e32 v101, v101
	v_exp_f32_e32 v102, v102
	v_exp_f32_e32 v103, v103
	v_mfma_f32_32x32x16_bf16 v[0:15], v[234:237], v[184:187], v[0:15]
	ds_read_b128 v[234:237], v174 offset:14912
	v_exp_f32_e32 v104, v104
	v_exp_f32_e32 v105, v105
	v_exp_f32_e32 v106, v106
	v_mfma_f32_32x32x16_bf16 v[32:47], v[230:233], v[188:191], v[32:47]
	ds_read_b128 v[230:233], v174 offset:10336
	v_exp_f32_e32 v107, v107
	v_exp_f32_e32 v108, v108
	v_exp_f32_e32 v109, v109
	v_mfma_f32_32x32x16_bf16 v[0:15], v[238:241], v[188:191], v[0:15]
	ds_read_b128 v[238:241], v174 offset:14944
	v_exp_f32_e32 v110, v110
	v_exp_f32_e32 v111, v111
	v_pk_add_f32 v[200:201], v[96:97], v[200:201]
	v_cvt_pk_bf16_f32 v176, v96, v97
	v_pk_add_f32 v[204:205], v[98:99], v[204:205]
	v_cvt_pk_bf16_f32 v177, v98, v99
	v_pk_add_f32 v[200:201], v[100:101], v[200:201]
	v_cvt_pk_bf16_f32 v178, v100, v101
	v_pk_add_f32 v[204:205], v[102:103], v[204:205]
	v_cvt_pk_bf16_f32 v179, v102, v103
	v_pk_add_f32 v[200:201], v[104:105], v[200:201]
	v_cvt_pk_bf16_f32 v180, v104, v105
	v_pk_add_f32 v[204:205], v[106:107], v[204:205]
	v_cvt_pk_bf16_f32 v181, v106, v107
	v_pk_add_f32 v[200:201], v[108:109], v[200:201]
	v_cvt_pk_bf16_f32 v182, v108, v109
	v_pk_add_f32 v[204:205], v[110:111], v[204:205]
	v_cvt_pk_bf16_f32 v183, v110, v111
	s_waitcnt lgkmcnt(4)
	v_mfma_f32_32x32x16_bf16 v[96:111], v[164:167], v[130:133], v[64:79]
	v_exp_f32_e32 v112, v112
	v_exp_f32_e32 v113, v113
	v_mfma_f32_32x32x16_bf16 v[96:111], v[168:171], v[134:137], v[96:111]
	ds_read_b128 v[164:167], v175 offset:24576
	ds_read_b128 v[168:171], v175 offset:24608
	v_exp_f32_e32 v114, v114
	v_exp_f32_e32 v115, v115
	v_exp_f32_e32 v116, v116
	s_waitcnt lgkmcnt(2)
	v_mfma_f32_32x32x16_bf16 v[48:63], v[226:229], v[176:179], v[48:63]
	v_exp_f32_e32 v117, v117
	v_exp_f32_e32 v118, v118
	v_exp_f32_e32 v119, v119
	v_mfma_f32_32x32x16_bf16 v[16:31], v[234:237], v[176:179], v[16:31]
	v_exp_f32_e32 v120, v120
	v_exp_f32_e32 v121, v121
	v_exp_f32_e32 v122, v122
	v_mfma_f32_32x32x16_bf16 v[48:63], v[230:233], v[180:183], v[48:63]
	v_exp_f32_e32 v123, v123
	v_exp_f32_e32 v124, v124
	v_exp_f32_e32 v125, v125
	v_mfma_f32_32x32x16_bf16 v[16:31], v[238:241], v[180:183], v[16:31]
	s_waitcnt vmcnt(1)
	ds_write_b128 v155, v[146:149] offset:38912
	s_waitcnt vmcnt(0)
	ds_write_b128 v157, v[150:153] offset:49152
	v_exp_f32_e32 v126, v126
	v_exp_f32_e32 v127, v127
	v_pk_add_f32 v[202:203], v[112:113], v[202:203]
	v_cvt_pk_bf16_f32 v184, v112, v113
	v_pk_add_f32 v[208:209], v[114:115], v[208:209]
	v_cvt_pk_bf16_f32 v185, v114, v115
	v_pk_add_f32 v[202:203], v[116:117], v[202:203]
	v_cvt_pk_bf16_f32 v186, v116, v117
	v_pk_add_f32 v[208:209], v[118:119], v[208:209]
	v_cvt_pk_bf16_f32 v187, v118, v119
	v_pk_add_f32 v[202:203], v[120:121], v[202:203]
	v_cvt_pk_bf16_f32 v188, v120, v121
	v_pk_add_f32 v[208:209], v[122:123], v[208:209]
	v_cvt_pk_bf16_f32 v189, v122, v123
	v_pk_add_f32 v[202:203], v[124:125], v[202:203]
	v_cvt_pk_bf16_f32 v190, v124, v125
	v_pk_add_f32 v[208:209], v[126:127], v[208:209]
	v_cvt_pk_bf16_f32 v191, v126, v127
	s_cmp_eq_u32 s2, 43
	s_cbranch_scc1 .Lat_skip1
	global_load_dwordx4 v[146:149], v192, s[0:1]
	global_load_dwordx4 v[150:153], v193, s[100:101]
	s_add_u32 s0, s0, s54
	s_addc_u32 s1, s1, s55
	s_add_u32 s100, s100, s88
	s_addc_u32 s101, s101, s89
.Lat_skip1:
	s_waitcnt lgkmcnt(2)
	v_mfma_f32_32x32x16_bf16 v[112:127], v[164:167], v[138:141], v[80:95]
	v_exp_f32_e32 v96, v96
	v_exp_f32_e32 v97, v97
	v_mfma_f32_32x32x16_bf16 v[112:127], v[168:171], v[142:145], v[112:127]
	ds_read_b128 v[164:167], v175 offset:22016
	ds_read_b128 v[168:171], v175 offset:22048
	v_exp_f32_e32 v98, v98
	v_exp_f32_e32 v99, v99
	v_exp_f32_e32 v100, v100
	v_mfma_f32_32x32x16_bf16 v[32:47], v[226:229], v[184:187], v[32:47]
	ds_read_b128 v[226:229], v174 offset:29696
	v_exp_f32_e32 v101, v101
	v_exp_f32_e32 v102, v102
	v_exp_f32_e32 v103, v103
	v_mfma_f32_32x32x16_bf16 v[0:15], v[234:237], v[184:187], v[0:15]
	ds_read_b128 v[234:237], v174 offset:34304
	v_exp_f32_e32 v104, v104
	v_exp_f32_e32 v105, v105
	v_exp_f32_e32 v106, v106
	v_mfma_f32_32x32x16_bf16 v[32:47], v[230:233], v[188:191], v[32:47]
	ds_read_b128 v[230:233], v174 offset:29728
	v_exp_f32_e32 v107, v107
	v_exp_f32_e32 v108, v108
	v_exp_f32_e32 v109, v109
	v_mfma_f32_32x32x16_bf16 v[0:15], v[238:241], v[188:191], v[0:15]
	ds_read_b128 v[238:241], v174 offset:34336
	v_exp_f32_e32 v110, v110
	v_exp_f32_e32 v111, v111
	v_pk_add_f32 v[200:201], v[96:97], v[200:201]
	v_cvt_pk_bf16_f32 v176, v96, v97
	v_pk_add_f32 v[204:205], v[98:99], v[204:205]
	v_cvt_pk_bf16_f32 v177, v98, v99
	v_pk_add_f32 v[200:201], v[100:101], v[200:201]
	v_cvt_pk_bf16_f32 v178, v100, v101
	v_pk_add_f32 v[204:205], v[102:103], v[204:205]
	v_cvt_pk_bf16_f32 v179, v102, v103
	v_pk_add_f32 v[200:201], v[104:105], v[200:201]
	v_cvt_pk_bf16_f32 v180, v104, v105
	v_pk_add_f32 v[204:205], v[106:107], v[204:205]
	v_cvt_pk_bf16_f32 v181, v106, v107
	v_pk_add_f32 v[200:201], v[108:109], v[200:201]
	v_cvt_pk_bf16_f32 v182, v108, v109
	v_pk_add_f32 v[204:205], v[110:111], v[204:205]
	v_cvt_pk_bf16_f32 v183, v110, v111
	s_waitcnt lgkmcnt(4)
	v_mfma_f32_32x32x16_bf16 v[96:111], v[164:167], v[130:133], v[64:79]
	v_exp_f32_e32 v112, v112
	v_exp_f32_e32 v113, v113
	v_mfma_f32_32x32x16_bf16 v[96:111], v[168:171], v[134:137], v[96:111]
	ds_read_b128 v[164:167], v175 offset:27136
	ds_read_b128 v[168:171], v175 offset:27168
	v_exp_f32_e32 v114, v114
	v_exp_f32_e32 v115, v115
	v_exp_f32_e32 v116, v116
	s_waitcnt lgkmcnt(2)
	v_mfma_f32_32x32x16_bf16 v[48:63], v[226:229], v[176:179], v[48:63]
	v_exp_f32_e32 v117, v117
	v_exp_f32_e32 v118, v118
	v_exp_f32_e32 v119, v119
	v_mfma_f32_32x32x16_bf16 v[16:31], v[234:237], v[176:179], v[16:31]
	v_exp_f32_e32 v120, v120
	v_exp_f32_e32 v121, v121
	v_exp_f32_e32 v122, v122
	v_mfma_f32_32x32x16_bf16 v[48:63], v[230:233], v[180:183], v[48:63]
	v_exp_f32_e32 v123, v123
	v_exp_f32_e32 v124, v124
	v_exp_f32_e32 v125, v125
	v_mfma_f32_32x32x16_bf16 v[16:31], v[238:241], v[180:183], v[16:31]
	v_exp_f32_e32 v126, v126
	v_exp_f32_e32 v127, v127
	v_pk_add_f32 v[202:203], v[112:113], v[202:203]
	v_cvt_pk_bf16_f32 v184, v112, v113
	v_pk_add_f32 v[208:209], v[114:115], v[208:209]
	v_cvt_pk_bf16_f32 v185, v114, v115
	v_pk_add_f32 v[202:203], v[116:117], v[202:203]
	v_cvt_pk_bf16_f32 v186, v116, v117
	v_pk_add_f32 v[208:209], v[118:119], v[208:209]
	v_cvt_pk_bf16_f32 v187, v118, v119
	v_pk_add_f32 v[202:203], v[120:121], v[202:203]
	v_cvt_pk_bf16_f32 v188, v120, v121
	v_pk_add_f32 v[208:209], v[122:123], v[208:209]
	v_cvt_pk_bf16_f32 v189, v122, v123
	v_pk_add_f32 v[202:203], v[124:125], v[202:203]
	v_cvt_pk_bf16_f32 v190, v124, v125
	v_pk_add_f32 v[208:209], v[126:127], v[208:209]
	v_cvt_pk_bf16_f32 v191, v126, v127
	s_waitcnt lgkmcnt(0)
	v_mfma_f32_32x32x16_bf16 v[112:127], v[164:167], v[138:141], v[80:95]
	v_exp_f32_e32 v96, v96
	v_exp_f32_e32 v97, v97
	v_mfma_f32_32x32x16_bf16 v[112:127], v[168:171], v[142:145], v[112:127]
	s_barrier
	ds_read_b128 v[164:167], v175 offset:38912
	ds_read_b128 v[168:171], v175 offset:38944
	v_exp_f32_e32 v98, v98
	v_exp_f32_e32 v99, v99
	v_exp_f32_e32 v100, v100
	v_mfma_f32_32x32x16_bf16 v[32:47], v[226:229], v[184:187], v[32:47]
	ds_read_b128 v[226:229], v174 offset:29760
	v_exp_f32_e32 v101, v101
	v_exp_f32_e32 v102, v102
	v_exp_f32_e32 v103, v103
	v_mfma_f32_32x32x16_bf16 v[0:15], v[234:237], v[184:187], v[0:15]
	ds_read_b128 v[234:237], v174 offset:34368
	v_exp_f32_e32 v104, v104
	v_exp_f32_e32 v105, v105
	v_exp_f32_e32 v106, v106
	v_mfma_f32_32x32x16_bf16 v[32:47], v[230:233], v[188:191], v[32:47]
	ds_read_b128 v[230:233], v174 offset:29792
	v_exp_f32_e32 v107, v107
	v_exp_f32_e32 v108, v108
	v_exp_f32_e32 v109, v109
	v_mfma_f32_32x32x16_bf16 v[0:15], v[238:241], v[188:191], v[0:15]
	ds_read_b128 v[238:241], v174 offset:34400
	v_exp_f32_e32 v110, v110
	v_exp_f32_e32 v111, v111
	v_pk_add_f32 v[200:201], v[96:97], v[200:201]
	v_cvt_pk_bf16_f32 v176, v96, v97
	v_pk_add_f32 v[204:205], v[98:99], v[204:205]
	v_cvt_pk_bf16_f32 v177, v98, v99
	v_pk_add_f32 v[200:201], v[100:101], v[200:201]
	v_cvt_pk_bf16_f32 v178, v100, v101
	v_pk_add_f32 v[204:205], v[102:103], v[204:205]
	v_cvt_pk_bf16_f32 v179, v102, v103
	v_pk_add_f32 v[200:201], v[104:105], v[200:201]
	v_cvt_pk_bf16_f32 v180, v104, v105
	v_pk_add_f32 v[204:205], v[106:107], v[204:205]
	v_cvt_pk_bf16_f32 v181, v106, v107
	v_pk_add_f32 v[200:201], v[108:109], v[200:201]
	v_cvt_pk_bf16_f32 v182, v108, v109
	v_pk_add_f32 v[204:205], v[110:111], v[204:205]
	v_cvt_pk_bf16_f32 v183, v110, v111
	s_waitcnt lgkmcnt(4)
	v_mfma_f32_32x32x16_bf16 v[96:111], v[164:167], v[130:133], v[64:79]
	v_exp_f32_e32 v112, v112
	v_exp_f32_e32 v113, v113
	v_mfma_f32_32x32x16_bf16 v[96:111], v[168:171], v[134:137], v[96:111]
	ds_read_b128 v[164:167], v175 offset:44032
	ds_read_b128 v[168:171], v175 offset:44064
	v_exp_f32_e32 v114, v114
	v_exp_f32_e32 v115, v115
	v_exp_f32_e32 v116, v116
	s_waitcnt lgkmcnt(2)
	v_mfma_f32_32x32x16_bf16 v[48:63], v[226:229], v[176:179], v[48:63]
	v_exp_f32_e32 v117, v117
	v_exp_f32_e32 v118, v118
	v_exp_f32_e32 v119, v119
	v_mfma_f32_32x32x16_bf16 v[16:31], v[234:237], v[176:179], v[16:31]
	v_exp_f32_e32 v120, v120
	v_exp_f32_e32 v121, v121
	v_exp_f32_e32 v122, v122
	v_mfma_f32_32x32x16_bf16 v[48:63], v[230:233], v[180:183], v[48:63]
	v_exp_f32_e32 v123, v123
	v_exp_f32_e32 v124, v124
	v_exp_f32_e32 v125, v125
	v_mfma_f32_32x32x16_bf16 v[16:31], v[238:241], v[180:183], v[16:31]
	s_waitcnt vmcnt(1)
	ds_write_b128 v155, v[146:149] offset:0
	s_waitcnt vmcnt(0)
	ds_write_b128 v157, v[150:153] offset:10240
	v_exp_f32_e32 v126, v126
	v_exp_f32_e32 v127, v127
	v_pk_add_f32 v[202:203], v[112:113], v[202:203]
	v_cvt_pk_bf16_f32 v184, v112, v113
	v_pk_add_f32 v[208:209], v[114:115], v[208:209]
	v_cvt_pk_bf16_f32 v185, v114, v115
	v_pk_add_f32 v[202:203], v[116:117], v[202:203]
	v_cvt_pk_bf16_f32 v186, v116, v117
	v_pk_add_f32 v[208:209], v[118:119], v[208:209]
	v_cvt_pk_bf16_f32 v187, v118, v119
	v_pk_add_f32 v[202:203], v[120:121], v[202:203]
	v_cvt_pk_bf16_f32 v188, v120, v121
	v_pk_add_f32 v[208:209], v[122:123], v[208:209]
	v_cvt_pk_bf16_f32 v189, v122, v123
	v_pk_add_f32 v[202:203], v[124:125], v[202:203]
	v_cvt_pk_bf16_f32 v190, v124, v125
	v_pk_add_f32 v[208:209], v[126:127], v[208:209]
	v_cvt_pk_bf16_f32 v191, v126, v127
	s_cmp_eq_u32 s2, 43
	s_cbranch_scc1 .Lat_skip2
	global_load_dwordx4 v[146:149], v192, s[0:1]
	global_load_dwordx4 v[150:153], v193, s[100:101]
	s_add_u32 s0, s0, s54
	s_addc_u32 s1, s1, s55
	s_add_u32 s100, s100, s88
	s_addc_u32 s101, s101, s89
.Lat_skip2:
	s_waitcnt lgkmcnt(2)
	v_mfma_f32_32x32x16_bf16 v[112:127], v[164:167], v[138:141], v[80:95]
	v_exp_f32_e32 v96, v96
	v_exp_f32_e32 v97, v97
	v_mfma_f32_32x32x16_bf16 v[112:127], v[168:171], v[142:145], v[112:127]
	ds_read_b128 v[164:167], v175 offset:41472
	ds_read_b128 v[168:171], v175 offset:41504
	v_exp_f32_e32 v98, v98
	v_exp_f32_e32 v99, v99
	v_exp_f32_e32 v100, v100
	v_mfma_f32_32x32x16_bf16 v[32:47], v[226:229], v[184:187], v[32:47]
	ds_read_b128 v[226:229], v174 offset:49152
	v_exp_f32_e32 v101, v101
	v_exp_f32_e32 v102, v102
	v_exp_f32_e32 v103, v103
	v_mfma_f32_32x32x16_bf16 v[0:15], v[234:237], v[184:187], v[0:15]
	ds_read_b128 v[234:237], v174 offset:53760
	v_exp_f32_e32 v104, v104
	v_exp_f32_e32 v105, v105
	v_exp_f32_e32 v106, v106
	v_mfma_f32_32x32x16_bf16 v[32:47], v[230:233], v[188:191], v[32:47]
	ds_read_b128 v[230:233], v174 offset:49184
	v_exp_f32_e32 v107, v107
	v_exp_f32_e32 v108, v108
	v_exp_f32_e32 v109, v109
	v_mfma_f32_32x32x16_bf16 v[0:15], v[238:241], v[188:191], v[0:15]
	ds_read_b128 v[238:241], v174 offset:53792
	v_exp_f32_e32 v110, v110
	v_exp_f32_e32 v111, v111
	v_pk_add_f32 v[200:201], v[96:97], v[200:201]
	v_cvt_pk_bf16_f32 v176, v96, v97
	v_pk_add_f32 v[204:205], v[98:99], v[204:205]
	v_cvt_pk_bf16_f32 v177, v98, v99
	v_pk_add_f32 v[200:201], v[100:101], v[200:201]
	v_cvt_pk_bf16_f32 v178, v100, v101
	v_pk_add_f32 v[204:205], v[102:103], v[204:205]
	v_cvt_pk_bf16_f32 v179, v102, v103
	v_pk_add_f32 v[200:201], v[104:105], v[200:201]
	v_cvt_pk_bf16_f32 v180, v104, v105
	v_pk_add_f32 v[204:205], v[106:107], v[204:205]
	v_cvt_pk_bf16_f32 v181, v106, v107
	v_pk_add_f32 v[200:201], v[108:109], v[200:201]
	v_cvt_pk_bf16_f32 v182, v108, v109
	v_pk_add_f32 v[204:205], v[110:111], v[204:205]
	v_cvt_pk_bf16_f32 v183, v110, v111
	s_waitcnt lgkmcnt(4)
	v_mfma_f32_32x32x16_bf16 v[96:111], v[164:167], v[130:133], v[64:79]
	v_exp_f32_e32 v112, v112
	v_exp_f32_e32 v113, v113
	v_mfma_f32_32x32x16_bf16 v[96:111], v[168:171], v[134:137], v[96:111]
	ds_read_b128 v[164:167], v175 offset:46592
	ds_read_b128 v[168:171], v175 offset:46624
	v_exp_f32_e32 v114, v114
	v_exp_f32_e32 v115, v115
	v_exp_f32_e32 v116, v116
	s_waitcnt lgkmcnt(2)
	v_mfma_f32_32x32x16_bf16 v[48:63], v[226:229], v[176:179], v[48:63]
	v_exp_f32_e32 v117, v117
	v_exp_f32_e32 v118, v118
	v_exp_f32_e32 v119, v119
	v_mfma_f32_32x32x16_bf16 v[16:31], v[234:237], v[176:179], v[16:31]
	v_exp_f32_e32 v120, v120
	v_exp_f32_e32 v121, v121
	v_exp_f32_e32 v122, v122
	v_mfma_f32_32x32x16_bf16 v[48:63], v[230:233], v[180:183], v[48:63]
	v_exp_f32_e32 v123, v123
	v_exp_f32_e32 v124, v124
	v_exp_f32_e32 v125, v125
	v_mfma_f32_32x32x16_bf16 v[16:31], v[238:241], v[180:183], v[16:31]
	v_exp_f32_e32 v126, v126
	v_exp_f32_e32 v127, v127
	v_pk_add_f32 v[202:203], v[112:113], v[202:203]
	v_cvt_pk_bf16_f32 v184, v112, v113
	v_pk_add_f32 v[208:209], v[114:115], v[208:209]
	v_cvt_pk_bf16_f32 v185, v114, v115
	v_pk_add_f32 v[202:203], v[116:117], v[202:203]
	v_cvt_pk_bf16_f32 v186, v116, v117
	v_pk_add_f32 v[208:209], v[118:119], v[208:209]
	v_cvt_pk_bf16_f32 v187, v118, v119
	v_pk_add_f32 v[202:203], v[120:121], v[202:203]
	v_cvt_pk_bf16_f32 v188, v120, v121
	v_pk_add_f32 v[208:209], v[122:123], v[208:209]
	v_cvt_pk_bf16_f32 v189, v122, v123
	v_pk_add_f32 v[202:203], v[124:125], v[202:203]
	v_cvt_pk_bf16_f32 v190, v124, v125
	v_pk_add_f32 v[208:209], v[126:127], v[208:209]
	v_cvt_pk_bf16_f32 v191, v126, v127
	s_waitcnt lgkmcnt(0)
	v_mfma_f32_32x32x16_bf16 v[112:127], v[164:167], v[138:141], v[80:95]
	v_exp_f32_e32 v96, v96
	v_exp_f32_e32 v97, v97
	v_mfma_f32_32x32x16_bf16 v[112:127], v[168:171], v[142:145], v[112:127]
	s_barrier
	ds_read_b128 v[164:167], v175 offset:0
	ds_read_b128 v[168:171], v175 offset:32
	v_exp_f32_e32 v98, v98
	v_exp_f32_e32 v99, v99
	v_exp_f32_e32 v100, v100
	v_mfma_f32_32x32x16_bf16 v[32:47], v[226:229], v[184:187], v[32:47]
	ds_read_b128 v[226:229], v174 offset:49216
	v_exp_f32_e32 v101, v101
	v_exp_f32_e32 v102, v102
	v_exp_f32_e32 v103, v103
	v_mfma_f32_32x32x16_bf16 v[0:15], v[234:237], v[184:187], v[0:15]
	ds_read_b128 v[234:237], v174 offset:53824
	v_exp_f32_e32 v104, v104
	v_exp_f32_e32 v105, v105
	v_exp_f32_e32 v106, v106
	v_mfma_f32_32x32x16_bf16 v[32:47], v[230:233], v[188:191], v[32:47]
	ds_read_b128 v[230:233], v174 offset:49248
	v_exp_f32_e32 v107, v107
	v_exp_f32_e32 v108, v108
	v_exp_f32_e32 v109, v109
	v_mfma_f32_32x32x16_bf16 v[0:15], v[238:241], v[188:191], v[0:15]
	ds_read_b128 v[238:241], v174 offset:53856
	v_exp_f32_e32 v110, v110
	v_exp_f32_e32 v111, v111
	v_pk_add_f32 v[200:201], v[96:97], v[200:201]
	v_cvt_pk_bf16_f32 v176, v96, v97
	v_pk_add_f32 v[204:205], v[98:99], v[204:205]
	v_cvt_pk_bf16_f32 v177, v98, v99
	v_pk_add_f32 v[200:201], v[100:101], v[200:201]
	v_cvt_pk_bf16_f32 v178, v100, v101
	v_pk_add_f32 v[204:205], v[102:103], v[204:205]
	v_cvt_pk_bf16_f32 v179, v102, v103
	v_pk_add_f32 v[200:201], v[104:105], v[200:201]
	v_cvt_pk_bf16_f32 v180, v104, v105
	v_pk_add_f32 v[204:205], v[106:107], v[204:205]
	v_cvt_pk_bf16_f32 v181, v106, v107
	v_pk_add_f32 v[200:201], v[108:109], v[200:201]
	v_cvt_pk_bf16_f32 v182, v108, v109
	v_pk_add_f32 v[204:205], v[110:111], v[204:205]
	v_cvt_pk_bf16_f32 v183, v110, v111
	s_waitcnt lgkmcnt(4)
	v_mfma_f32_32x32x16_bf16 v[96:111], v[164:167], v[130:133], v[64:79]
	v_exp_f32_e32 v112, v112
	v_exp_f32_e32 v113, v113
	v_mfma_f32_32x32x16_bf16 v[96:111], v[168:171], v[134:137], v[96:111]
	ds_read_b128 v[164:167], v175 offset:5120
	ds_read_b128 v[168:171], v175 offset:5152
	v_exp_f32_e32 v114, v114
	v_exp_f32_e32 v115, v115
	v_exp_f32_e32 v116, v116
	s_waitcnt lgkmcnt(2)
	v_mfma_f32_32x32x16_bf16 v[48:63], v[226:229], v[176:179], v[48:63]
	v_exp_f32_e32 v117, v117
	v_exp_f32_e32 v118, v118
	v_exp_f32_e32 v119, v119
	v_mfma_f32_32x32x16_bf16 v[16:31], v[234:237], v[176:179], v[16:31]
	v_exp_f32_e32 v120, v120
	v_exp_f32_e32 v121, v121
	v_exp_f32_e32 v122, v122
	v_mfma_f32_32x32x16_bf16 v[48:63], v[230:233], v[180:183], v[48:63]
	v_exp_f32_e32 v123, v123
	v_exp_f32_e32 v124, v124
	v_exp_f32_e32 v125, v125
	v_mfma_f32_32x32x16_bf16 v[16:31], v[238:241], v[180:183], v[16:31]
	s_waitcnt vmcnt(1)
	ds_write_b128 v155, v[146:149] offset:19456
	s_waitcnt vmcnt(0)
	ds_write_b128 v157, v[150:153] offset:29696
	v_exp_f32_e32 v126, v126
	v_exp_f32_e32 v127, v127
	v_pk_add_f32 v[202:203], v[112:113], v[202:203]
	v_cvt_pk_bf16_f32 v184, v112, v113
	v_pk_add_f32 v[208:209], v[114:115], v[208:209]
	v_cvt_pk_bf16_f32 v185, v114, v115
	v_pk_add_f32 v[202:203], v[116:117], v[202:203]
	v_cvt_pk_bf16_f32 v186, v116, v117
	v_pk_add_f32 v[208:209], v[118:119], v[208:209]
	v_cvt_pk_bf16_f32 v187, v118, v119
	v_pk_add_f32 v[202:203], v[120:121], v[202:203]
	v_cvt_pk_bf16_f32 v188, v120, v121
	v_pk_add_f32 v[208:209], v[122:123], v[208:209]
	v_cvt_pk_bf16_f32 v189, v122, v123
	v_pk_add_f32 v[202:203], v[124:125], v[202:203]
	v_cvt_pk_bf16_f32 v190, v124, v125
	v_pk_add_f32 v[208:209], v[126:127], v[208:209]
	v_cvt_pk_bf16_f32 v191, v126, v127
	s_add_i32 s2, s2, 1
	s_cmp_lg_u32 s2, 44
	s_cbranch_scc1 .Lat_loop
	v_mfma_f32_32x32x16_bf16 v[32:47], v[226:229], v[184:187], v[32:47]
	v_mfma_f32_32x32x16_bf16 v[0:15], v[234:237], v[184:187], v[0:15]
	v_mfma_f32_32x32x16_bf16 v[32:47], v[230:233], v[188:191], v[32:47]
	v_mfma_f32_32x32x16_bf16 v[0:15], v[238:241], v[188:191], v[0:15]
	s_waitcnt lgkmcnt(0)
	v_pk_add_f32 v[200:201], v[204:205], v[200:201]
	v_pk_add_f32 v[202:203], v[208:209], v[202:203]
	v_add_f32_e32 v158, v200, v201
	v_add_f32_e32 v159, v202, v203
	s_branch .LBB0_604
